# prep phase: V transpose loop rewritten by hand with next-item prefetch
# baseline (speedup 1.0000x reference)
; #define LAS __attribute__((address_space(3)))
; __device__ __forceinline__ void phase_prep(LAS unsigned char* lds, const bf16_t* p5, bf16_t* xc, bf16_t* vt, const float* cw, const float* cb) {
;     ...
;     LAS bf16_t* tl = (LAS bf16_t*)lds;
;     for (int it = blockIdx.x; it < 32 * 65; it += gridDim.x) {
;         const int bh = it / 65, tb = it - bh * 65, b = bh >> 3, h = bh & 7;
;         __syncthreads();
; #pragma unroll
;         for (int i = 0; i < 2; ++i) { const int id = tid + 512 * i, row = id >> 4, c16 = id & 15;
;             const u32x4 a = *(const u32x4*)(p5 + ((size_t)b * TP + tb * 64 + row) * LDP + C_V + h * 128 + c16 * 8);
;             LAS unsigned* d = (LAS unsigned*)(tl + row * 130 + c16 * 8); d[0] = a.x; d[1] = a.y; d[2] = a.z; d[3] = a.w; }
;         __syncthreads();
; #pragma unroll
;         for (int i = 0; i < 2; ++i) { const int id = tid + 512 * i, dv = id >> 3, c8 = id & 7; unsigned short e[8];
; #pragma unroll
;             for (int j = 0; j < 8; ++j) e[j] = tl[(c8 * 8 + j) * 130 + dv];
;             u32x4 w; w.x = e[0] | ((unsigned)e[1] << 16); w.y = e[2] | ((unsigned)e[3] << 16); w.z = e[4] | ((unsigned)e[5] << 16); w.w = e[6] | ((unsigned)e[7] << 16);
;             *(u32x4*)(vt + ((size_t)bh * 128 + dv) * TP + tb * 64 + c8 * 8) = w; }
;     }
.LBB0_423:
	s_or_b64 exec, exec, s[16:17]
	v_readlane_b32 s0, v253, 1
	v_readlane_b32 s1, v253, 2
	s_andn2_b64 vcc, exec, s[0:1]
	s_cbranch_vccnz .LBB0_426
	s_movk_i32 s28, 0x2800
	s_movk_i32 s30, 0x104
	s_movk_i32 s32, 0x820
	s_movk_i32 s16, 0x2080
	v_lshrrev_b32_e32 v20, 4, v14
	v_and_b32_e32 v21, 15, v14
	v_lshlrev_b32_e32 v22, 4, v21
	v_mad_u32_u24 v23, v20, s28, v22
	v_add_u32_e32 v24, 0x50000, v23
	v_mad_u32_u24 v25, v20, s30, v22
	v_add_u32_e32 v26, 0x2080, v25
	v_lshrrev_b32_e32 v27, 3, v14
	v_and_b32_e32 v28, 7, v14
	v_lshlrev_b32_e32 v29, 1, v27
	v_mad_u32_u24 v30, v28, s32, v29
	v_lshlrev_b32_e32 v31, 4, v28
	v_mad_u32_u24 v32, v27, s16, v31
	v_add_u32_e32 v33, 0x82000, v32
	s_add_u32 s46, s14, 0x21000000
	s_addc_u32 s47, s15, 0
	s_mov_b32 s50, s2
	s_mul_hi_u32 s51, s50, 0x7e07e07f
	s_lshr_b32 s51, s51, 5
	s_mul_i32 s52, s51, 0x41
	s_sub_u32 s52, s50, s52
	s_lshr_b32 s53, s51, 3
	s_mul_i32 s53, s53, 0x1040
	s_lshl_b32 s54, s52, 6
	s_add_u32 s53, s53, s54
	s_mul_i32 s53, s53, 0x2800
	s_and_b32 s54, s51, 7
	s_lshl_b32 s54, s54, 8
	s_add_u32 s53, s53, s54
	s_add_u32 s53, s53, 0x2000
	s_mul_i32 s55, s51, 0x104000
	s_lshl_b32 s54, s52, 7
	s_add_u32 s55, s55, s54
	v_add_u32_e32 v34, s53, v23
	v_add_u32_e32 v35, s53, v24
	global_load_dwordx4 v[36:39], v34, s[4:5]
	global_load_dwordx4 v[40:43], v35, s[4:5]
	s_waitcnt vmcnt(0)
.Lvt_loop:
	s_barrier
	ds_write2_b32 v25, v36, v37 offset1:1
	ds_write2_b32 v25, v38, v39 offset0:2 offset1:3
	ds_write2_b32 v26, v40, v41 offset1:1
	ds_write2_b32 v26, v42, v43 offset0:2 offset1:3
	s_mov_b32 s59, s55
	s_add_u32 s50, s50, 0x100
	s_mul_hi_u32 s51, s50, 0x7e07e07f
	s_lshr_b32 s51, s51, 5
	s_mul_i32 s52, s51, 0x41
	s_sub_u32 s52, s50, s52
	s_lshr_b32 s53, s51, 3
	s_mul_i32 s53, s53, 0x1040
	s_lshl_b32 s54, s52, 6
	s_add_u32 s53, s53, s54
	s_mul_i32 s53, s53, 0x2800
	s_and_b32 s54, s51, 7
	s_lshl_b32 s54, s54, 8
	s_add_u32 s53, s53, s54
	s_add_u32 s53, s53, 0x2000
	s_mul_i32 s55, s51, 0x104000
	s_lshl_b32 s54, s52, 7
	s_add_u32 s55, s55, s54
	v_add_u32_e32 v34, s53, v23
	v_add_u32_e32 v35, s53, v24
	s_waitcnt lgkmcnt(0)
	global_load_dwordx4 v[36:39], v34, s[4:5]
	global_load_dwordx4 v[40:43], v35, s[4:5]
	s_barrier
	ds_read_u16 v44, v30
	ds_read_u16 v45, v30 offset:260
	ds_read_u16 v46, v30 offset:520
	ds_read_u16 v47, v30 offset:780
	ds_read_u16 v48, v30 offset:1040
	ds_read_u16 v49, v30 offset:1300
	ds_read_u16 v50, v30 offset:1560
	ds_read_u16 v51, v30 offset:1820
	ds_read_u16 v52, v30 offset:128
	ds_read_u16 v53, v30 offset:388
	ds_read_u16 v54, v30 offset:648
	ds_read_u16 v55, v30 offset:908
	ds_read_u16 v56, v30 offset:1168
	ds_read_u16 v57, v30 offset:1428
	ds_read_u16 v58, v30 offset:1688
	ds_read_u16 v59, v30 offset:1948
	v_add_u32_e32 v68, s59, v32
	v_add_u32_e32 v69, s59, v33
	s_waitcnt lgkmcnt(8)
	v_lshl_or_b32 v60, v45, 16, v44
	v_lshl_or_b32 v61, v47, 16, v46
	v_lshl_or_b32 v62, v49, 16, v48
	v_lshl_or_b32 v63, v51, 16, v50
	global_store_dwordx4 v68, v[60:63], s[46:47]
	s_waitcnt lgkmcnt(0)
	v_lshl_or_b32 v64, v53, 16, v52
	v_lshl_or_b32 v65, v55, 16, v54
	v_lshl_or_b32 v66, v57, 16, v56
	v_lshl_or_b32 v67, v59, 16, v58
	global_store_dwordx4 v69, v[64:67], s[46:47]
	s_waitcnt vmcnt(2)
	s_cmpk_lt_u32 s50, 0x820
	s_cbranch_scc1 .Lvt_loop
